# v9 plus scan loop: b-set gl in dedicated VGPR, back-edge waits only for a-set (two steps of prefetch lead for both sets)
# speedup vs baseline: 1.0081x; 1.0036x over previous
; __device__ __forceinline__ void step_part1(char* sm, int off_ut, f32x4& o) {
;   const int tid_ = opq(threadIdx.x);
;   const int lane = tid_ & 63, w = tid_ >> 6, r = lane & 15, q = lane >> 4;
;   const int mj = w >> 1, nd = w & 1;
;   const bfraw* wl = (const bfraw*)(sm + L_W);
;   const bfraw* qg = (const bfraw*)(sm + L_QG);
;   const bfraw* uT = (const bfraw*)(sm + off_ut);
;   const bfraw* St = (const bfraw*)(sm + L_ST);
;   bfraw* dltT = (bfraw*)(sm + L_DLT);
;   f32x4 dl = (f32x4){0.f, 0.f, 0.f, 0.f};
;   o = (f32x4){0.f, 0.f, 0.f, 0.f};
; #pragma unroll
;   for (int kk = 0; kk < 4; ++kk) {
;     bf16x8 sb = *(const bf16x8*)(St + (nd * 16 + r) * 136 + kk * 32 + q * 8);
;     bf16x8 aw = *(const bf16x8*)(wl + (mj * 16 + r) * 136 + kk * 32 + q * 8);
;     bf16x8 aq = *(const bf16x8*)(qg + (mj * 16 + r) * 136 + kk * 32 + q * 8);
;     dl = mfma16(aw, sb, dl);
;     o = mfma16(aq, sb, o);
;   }
;   uint2 uv = *(const uint2*)(uT + (nd * 16 + r) * 72 + mj * 16 + q * 4);
;   uint2 dv;
;   dv.x = pack2(lo2f(uv.x) - dl[0], hi2f(uv.x) - dl[1]);
;   dv.y = pack2(lo2f(uv.y) - dl[2], hi2f(uv.y) - dl[3]);
;   *(uint2*)(dltT + (nd * 16 + r) * 72 + mj * 16 + q * 4) = dv;
; }
; __device__ __forceinline__ void step_part2(const Params& p, char* sm, int off_kgt, int off_qk, int h, int s, int grow0, int nvalid,
;                                            float gl, f32x4& o, f32x4 (&S)[2]) {
;   const int tid_ = opq(threadIdx.x);
;   const int lane = tid_ & 63, w = tid_ >> 6, r = lane & 15, q = lane >> 4;
;   const int mj = w >> 1, nd = w & 1;
;   const bfraw* kgT = (const bfraw*)(sm + off_kgt);
;   const bfraw* qk = (const bfraw*)(sm + off_qk);
;   const bfraw* dltT = (const bfraw*)(sm + L_DLT);
; #pragma unroll
;   for (int g = 0; g < 4; ++g) { S[0][g] *= gl; S[1][g] *= gl; }
; #pragma unroll
;   for (int kk = 0; kk < 2; ++kk) {
;     bf16x8 d0 = *(const bf16x8*)(dltT + (r) * 72 + kk * 32 + q * 8);
; __device__ __forceinline__ void scan_unit(const Params& p, int l, int bhs, char* sm) {
;     ...
;   PRE_LOAD(a, gla, 0)
;   PRE_LOAD(b, glb, 1)
;   for (int c = 0; c < NCH; c += 2) {
;     LDS_PUT(a, 0)
;     const float gl0 = gla;
;     PRE_LOAD(a, gla, c + 2)
;     SCAN_STEP(c, 0, gl0)
;     if (c + 1 < NCH) {
;       LDS_PUT(b, 1)
;       const float gl1 = glb;
;       PRE_LOAD(b, glb, c + 3)
;       SCAN_STEP(c + 1, 1, gl1)
.LBB0_1583:
	s_or_b64 exec, exec, s[10:11]
	s_mul_i32 s21, s14, 0x81
	s_add_i32 s28, s21, 3
	s_lshl_b32 s10, s28, 2
	s_or_b32 s13, s10, s15
	s_mul_i32 s10, s13, 0x12000
	s_mul_hi_u32 s11, s13, 0x12000
	s_add_u32 s10, s8, s10
	s_addc_u32 s11, s9, s11
	s_waitcnt vmcnt(10)
	v_lshl_add_u64 v[56:57], v[82:83], 1, s[10:11]
	v_add_co_u32_e32 v36, vcc, 0x2000, v56
	s_nop 1
	v_addc_co_u32_e32 v37, vcc, 0, v57, vcc
	v_add_co_u32_e32 v40, vcc, 0x4000, v56
	global_load_dwordx4 v[32:35], v[56:57], off
	s_nop 0
	global_load_dwordx4 v[36:39], v[36:37], off
	v_addc_co_u32_e32 v41, vcc, 0, v57, vcc
	v_add_co_u32_e32 v44, vcc, 0x6000, v56
	s_nop 1
	v_addc_co_u32_e32 v45, vcc, 0, v57, vcc
	v_add_co_u32_e32 v48, vcc, 0x8000, v56
	global_load_dwordx4 v[40:43], v[40:41], off
	s_nop 0
	global_load_dwordx4 v[44:47], v[44:45], off
	v_addc_co_u32_e32 v49, vcc, 0, v57, vcc
	v_add_co_u32_e32 v52, vcc, 0xa000, v56
	s_nop 1
	v_addc_co_u32_e32 v53, vcc, 0, v57, vcc
	v_add_co_u32_e32 v58, vcc, 0xc000, v56
	global_load_dwordx4 v[48:51], v[48:49], off
	s_nop 0
	global_load_dwordx4 v[52:55], v[52:53], off
	v_addc_co_u32_e32 v59, vcc, 0, v57, vcc
	v_lshl_add_u64 v[56:57], v[56:57], 0, s[0:1]
	v_lshl_add_u64 v[56:57], v[76:77], 1, v[56:57]
	v_add_co_u32_e32 v56, vcc, 0xe000, v56
	s_lshl_b32 s1, s13, 2
	s_nop 0
	v_addc_co_u32_e32 v57, vcc, 0, v57, vcc
	v_mov_b32_e32 v72, s1
	global_load_dwordx4 v[60:63], v[58:59], off
	s_nop 0
	global_load_dwordx4 v[56:59], v[56:57], off
	s_movk_i32 s1, 0x110
	global_load_dword v225, v72, s[4:5]
	v_mov_b32_e32 v72, v224
	s_waitcnt lgkmcnt(0)
	s_barrier
	s_nop 0
	v_ashrrev_i32_e32 v116, 3, v72
	v_and_b32_e32 v79, 15, v72
	v_bfe_u32 v81, v72, 4, 2
	v_lshrrev_b32_e32 v85, 2, v72
	v_bfi_b32 v72, -16, v116, v72
	v_lshlrev_b32_e32 v91, 4, v81
	v_mul_lo_u32 v72, v72, s1
	v_add3_u32 v112, 0, v72, v91
	ds_read_b128 v[72:75], v112
	v_and_or_b32 v79, v85, 16, v79
	v_mul_u32_u24_e32 v85, 0x110, v79
	v_add3_u32 v85, s16, v85, v91
	ds_read_b128 v[92:95], v85
	ds_read_b128 v[96:99], v85 offset:64
	ds_read_b128 v[100:103], v112 offset:64
	s_waitcnt lgkmcnt(2)
	v_mfma_f32_16x16x32_bf16 v[72:75], v[72:75], v[92:95], 0
	ds_read_b128 v[104:107], v112 offset:17408
	ds_read_b128 v[108:111], v112 offset:17472
	v_mul_u32_u24_e32 v79, 0x48, v79
	v_lshlrev_b32_e32 v79, 1, v79
	s_waitcnt lgkmcnt(2)
	v_mfma_f32_16x16x32_bf16 v[72:75], v[100:103], v[96:99], v[72:75]
	ds_read_b128 v[100:103], v112 offset:128
	v_lshlrev_b32_e32 v81, 3, v81
	v_add_u32_e32 v91, 0, v79
	s_waitcnt lgkmcnt(2)
	v_mfma_f32_16x16x32_bf16 v[92:95], v[104:107], v[92:95], 0
	s_movk_i32 s1, 0x90
	s_waitcnt lgkmcnt(1)
	v_mfma_f32_16x16x32_bf16 v[92:95], v[108:111], v[96:99], v[92:95]
	ds_read_b128 v[96:99], v85 offset:128
	ds_read_b128 v[104:107], v85 offset:192
	ds_read_b128 v[108:111], v112 offset:192
	v_and_b32_e32 v85, -16, v116
	v_lshlrev_b32_e32 v85, 1, v85
	s_waitcnt lgkmcnt(2)
	v_mfma_f32_16x16x32_bf16 v[72:75], v[100:103], v[96:99], v[72:75]
	ds_read_b128 v[100:103], v112 offset:17536
	ds_read_b128 v[112:115], v112 offset:17600
	v_add3_u32 v91, v91, v85, v81
	s_waitcnt lgkmcnt(1)
	v_mfma_f32_16x16x32_bf16 v[92:95], v[100:103], v[96:99], v[92:95]
	ds_read_b64 v[96:97], v91 offset:62464
	s_waitcnt lgkmcnt(0)
	v_lshlrev_b32_e32 v98, 16, v96
	v_mfma_f32_16x16x32_bf16 v[72:75], v[108:111], v[104:107], v[72:75]
	v_and_b32_e32 v99, 0xffff0000, v96
	v_lshlrev_b32_e32 v96, 16, v97
	v_and_b32_e32 v97, 0xffff0000, v97
	v_mfma_f32_16x16x32_bf16 v[92:95], v[112:115], v[104:107], v[92:95]
	s_nop 3
	v_add_f32_e64 v72, v98, -v72
	v_add_f32_e64 v73, v99, -v73
	v_pk_add_f32 v[74:75], v[96:97], v[74:75] neg_lo:[0,1] neg_hi:[0,1]
	v_cvt_pk_bf16_f32 v72, v72, v73
	v_cvt_pk_bf16_f32 v73, v74, v75
	v_add_u32_e32 v74, s17, v79
	v_add3_u32 v74, v74, v85, v81
	ds_write_b64 v74, v[72:73]
	v_mov_b32_e32 v72, v224
	s_waitcnt lgkmcnt(0)
	s_barrier
	s_nop 0
	v_ashrrev_i32_e32 v124, 3, v72
	v_ashrrev_i32_e32 v73, 6, v72
	v_and_b32_e32 v81, 15, v72
	v_bfe_u32 v79, v72, 4, 2
	v_bfi_b32 v72, -16, v124, v72
	v_lshlrev_b32_e32 v75, 4, v79
	v_mul_lo_u32 v72, v72, s1
	v_mul_u32_u24_e32 v74, 0x90, v81
	v_add3_u32 v120, s20, v72, v75
	v_lshl_or_b32 v72, v73, 4, v81
	v_and_b32_e32 v91, 1, v73
	v_add3_u32 v85, s17, v74, v75
	v_mul_lo_u32 v72, v72, s1
	v_add3_u32 v125, s19, v72, v75
	ds_read_b128 v[72:75], v85
	ds_read_b128 v[96:99], v85 offset:2304
	ds_read_b128 v[100:103], v120
	ds_read_b128 v[104:107], v125
	ds_read_b128 v[108:111], v85 offset:64
	ds_read_b128 v[112:115], v85 offset:2368
	v_cmp_eq_u32_e32 vcc, 0, v91
	ds_read_b128 v[120:123], v120 offset:64
	s_waitcnt vmcnt(18)
	v_pk_mul_f32 v[70:71], v[84:85], v[70:71] op_sel_hi:[0,1]
	s_waitcnt lgkmcnt(5)
	v_cndmask_b32_e32 v119, v99, v75, vcc
	v_cndmask_b32_e32 v118, v98, v74, vcc
	v_cndmask_b32_e32 v117, v97, v73, vcc
	v_cndmask_b32_e32 v116, v96, v72, vcc
	v_pk_mul_f32 v[68:69], v[84:85], v[68:69] op_sel_hi:[0,1]
	v_pk_mul_f32 v[66:67], v[84:85], v[66:67] op_sel_hi:[0,1]
	s_waitcnt lgkmcnt(4)
	v_mfma_f32_16x16x32_bf16 v[92:95], v[100:103], v[116:119], v[92:95]
	ds_read_b128 v[100:103], v125 offset:64
	v_pk_mul_f32 v[64:65], v[84:85], v[64:65] op_sel_hi:[0,1]
	v_mov_b32_e32 v84, v224
	s_waitcnt lgkmcnt(4)
	v_mfma_f32_16x16x32_bf16 v[68:71], v[104:107], v[72:75], v[68:71]
	s_waitcnt lgkmcnt(2)
	v_cndmask_b32_e32 v75, v115, v111, vcc
	v_cndmask_b32_e32 v74, v114, v110, vcc
	v_cndmask_b32_e32 v73, v113, v109, vcc
	v_mfma_f32_16x16x32_bf16 v[64:67], v[104:107], v[96:99], v[64:67]
	v_cndmask_b32_e32 v72, v112, v108, vcc
	s_add_i32 s1, s18, 16
	s_waitcnt lgkmcnt(0)
	v_mfma_f32_16x16x32_bf16 v[68:71], v[100:103], v[108:111], v[68:71]
	v_and_b32_e32 v85, 15, v84
	v_mul_u32_u24_e32 v85, 0x110, v85
	v_mfma_f32_16x16x32_bf16 v[72:75], v[120:123], v[72:75], v[92:95]
	s_nop 2
	v_ashrrev_i32_e32 v93, 2, v84
	v_mfma_f32_16x16x32_bf16 v[64:67], v[100:103], v[112:115], v[64:67]
	v_lshlrev_b32_e32 v93, 1, v93
	v_and_b32_e32 v93, 0xffffffe0, v93
	v_lshrrev_b32_e32 v84, 1, v84
	v_add_u32_e32 v93, s16, v93
	v_and_b32_e32 v84, 24, v84
	v_add3_u32 v93, v93, v84, v85
	v_cvt_pk_bf16_f32 v85, v70, v71
	v_cvt_pk_bf16_f32 v84, v68, v69
	ds_write_b64 v93, v[84:85]
	v_cvt_pk_bf16_f32 v85, v66, v67
	v_cvt_pk_bf16_f32 v84, v64, v65
	v_and_b32_e32 v92, -16, v124
	ds_write_b64 v93, v[84:85] offset:4352
	v_lshlrev_b32_e32 v84, 5, v91
	v_mov_b32_e32 v85, 0
	v_lshl_or_b32 v79, v79, 2, v92
	v_lshl_add_u64 v[92:93], s[6:7], 0, v[84:85]
	v_lshlrev_b32_e32 v84, 1, v81
	v_lshl_add_u64 v[84:85], v[92:93], 0, v[84:85]
	v_cmp_gt_i32_e32 vcc, 64, v79
	s_and_saveexec_b64 s[10:11], vcc
	s_cbranch_execz .LBB0_1585
	v_add_u32_e32 v92, s1, v79
	v_ashrrev_i32_e32 v93, 31, v92
	v_lshlrev_b64 v[92:93], 12, v[92:93]
	v_lshl_add_u64 v[92:93], v[84:85], 0, v[92:93]
	v_cvt_pk_bf16_f32 v72, v72, s0
	global_store_short v[92:93], v72, off

; #define SCAN_STEP(C, KB, GLV) { \
;     __syncthreads(); \
;     int t0_, nv_; \
;     if ((C) == 0) { t0_ = 0; nv_ = 16; } else { t0_ = 16 + ((C) - 1) * 64; nv_ = 64; } \
;     f32x4 o_; \
;     step_part1(sm, L_UT, o_); \
;     __syncthreads(); \
;     step_part2(p, sm, (KB) ? L_KGT2 : L_KGT, (KB) ? L_QK2 : L_QK, h, s, b * TP + t0_, nv_, GLV, o_, S); }
; __device__ __forceinline__ void scan_unit(const Params& p, int l, int bhs, char* sm) {
;     ...
;   for (int c = 0; c < NCH; c += 2) {
;     LDS_PUT(a, 0)
;     const float gl0 = gla;
;     PRE_LOAD(a, gla, c + 2)
;     SCAN_STEP(c, 0, gl0)
;     if (c + 1 < NCH) {
;       LDS_PUT(b, 1)
;       const float gl1 = glb;
;       PRE_LOAD(b, glb, c + 3)
.LBB0_1593:
	s_mov_b32 s8, s34
	s_waitcnt vmcnt(13)
	v_mov_b32_e32 v80, v92

; __device__ __forceinline__ void step_part1(char* sm, int off_ut, f32x4& o) {
;   const int tid_ = opq(threadIdx.x);
;   const int lane = tid_ & 63, w = tid_ >> 6, r = lane & 15, q = lane >> 4;
;   const int mj = w >> 1, nd = w & 1;
;   const bfraw* wl = (const bfraw*)(sm + L_W);
;   const bfraw* qg = (const bfraw*)(sm + L_QG);
;   const bfraw* uT = (const bfraw*)(sm + off_ut);
;   const bfraw* St = (const bfraw*)(sm + L_ST);
;   bfraw* dltT = (bfraw*)(sm + L_DLT);
;   f32x4 dl = (f32x4){0.f, 0.f, 0.f, 0.f};
;   o = (f32x4){0.f, 0.f, 0.f, 0.f};
; #pragma unroll
;   for (int kk = 0; kk < 4; ++kk) {
;     bf16x8 sb = *(const bf16x8*)(St + (nd * 16 + r) * 136 + kk * 32 + q * 8);
;     bf16x8 aw = *(const bf16x8*)(wl + (mj * 16 + r) * 136 + kk * 32 + q * 8);
;     bf16x8 aq = *(const bf16x8*)(qg + (mj * 16 + r) * 136 + kk * 32 + q * 8);
;     dl = mfma16(aw, sb, dl);
;     o = mfma16(aq, sb, o);
;   }
;   uint2 uv = *(const uint2*)(uT + (nd * 16 + r) * 72 + mj * 16 + q * 4);
;   uint2 dv;
;   dv.x = pack2(lo2f(uv.x) - dl[0], hi2f(uv.x) - dl[1]);
;   dv.y = pack2(lo2f(uv.y) - dl[2], hi2f(uv.y) - dl[3]);
;   *(uint2*)(dltT + (nd * 16 + r) * 72 + mj * 16 + q * 4) = dv;
; }
; __device__ __forceinline__ void step_part2(const Params& p, char* sm, int off_kgt, int off_qk, int h, int s, int grow0, int nvalid,
;                                            float gl, f32x4& o, f32x4 (&S)[2]) {
;   const int tid_ = opq(threadIdx.x);
;   const int lane = tid_ & 63, w = tid_ >> 6, r = lane & 15, q = lane >> 4;
;   const int mj = w >> 1, nd = w & 1;
;   const bfraw* kgT = (const bfraw*)(sm + off_kgt);
;   const bfraw* qk = (const bfraw*)(sm + off_qk);
;   const bfraw* dltT = (const bfraw*)(sm + L_DLT);
; #pragma unroll
;   for (int g = 0; g < 4; ++g) { S[0][g] *= gl; S[1][g] *= gl; }
; #pragma unroll
;   for (int kk = 0; kk < 2; ++kk) {
;     bf16x8 d0 = *(const bf16x8*)(dltT + (r) * 72 + kk * 32 + q * 8);
;     bf16x8 d1 = *(const bf16x8*)(dltT + (16 + r) * 72 + kk * 32 + q * 8);
;     bf16x8 aqk = *(const bf16x8*)(qk + (mj * 16 + r) * 72 + kk * 32 + q * 8);
;     bf16x8 ak = *(const bf16x8*)(kgT + (w * 16 + r) * 72 + kk * 32 + q * 8);
; __device__ __forceinline__ void scan_unit(const Params& p, int l, int bhs, char* sm) {
;     ...
;     if (c + 1 < NCH) {
;       LDS_PUT(b, 1)
;       const float gl1 = glb;
;       PRE_LOAD(b, glb, c + 3)
;       SCAN_STEP(c + 1, 1, gl1)
.LBB0_1607:
	s_or_b64 exec, exec, s[12:13]
	s_min_u32 s8, s34, 0x7d
	s_add_i32 s8, s8, s28
	s_lshl_b32 s8, s8, 2
	s_or_b32 s8, s8, s15
	s_waitcnt vmcnt(10)
	v_mov_b32_e32 v78, v225
	v_mad_u64_u32 v[56:57], s[12:13], s8, v91, v[82:83]
	v_add_co_u32_e32 v36, vcc, 0x2000, v56
	s_lshl_b32 s8, s8, 2
	s_nop 0
	v_addc_co_u32_e32 v37, vcc, 0, v57, vcc
	v_add_co_u32_e32 v40, vcc, 0x4000, v56
	global_load_dwordx4 v[32:35], v[56:57], off
	s_nop 0
	global_load_dwordx4 v[36:39], v[36:37], off
	v_addc_co_u32_e32 v41, vcc, 0, v57, vcc
	v_add_co_u32_e32 v44, vcc, 0x6000, v56
	v_mov_b32_e32 v72, s8
	s_nop 0
	v_addc_co_u32_e32 v45, vcc, 0, v57, vcc
	v_add_co_u32_e32 v48, vcc, 0x8000, v56
	global_load_dwordx4 v[40:43], v[40:41], off
	s_nop 0
	global_load_dwordx4 v[44:47], v[44:45], off
	v_addc_co_u32_e32 v49, vcc, 0, v57, vcc
	v_add_co_u32_e32 v52, vcc, 0xa000, v56
	s_nop 1
	v_addc_co_u32_e32 v53, vcc, 0, v57, vcc
	v_add_co_u32_e32 v58, vcc, 0xc000, v56
	global_load_dwordx4 v[48:51], v[48:49], off
	s_nop 0
	global_load_dwordx4 v[52:55], v[52:53], off
	v_addc_co_u32_e32 v59, vcc, 0, v57, vcc
	v_lshl_add_u64 v[56:57], v[56:57], 0, s[0:1]
	v_lshl_add_u64 v[56:57], v[76:77], 1, v[56:57]
	v_add_co_u32_e32 v56, vcc, 0xe000, v56
	s_nop 1
	v_addc_co_u32_e32 v57, vcc, 0, v57, vcc
	global_load_dwordx4 v[60:63], v[58:59], off
	s_nop 0
	global_load_dwordx4 v[56:59], v[56:57], off
	s_nop 0
	global_load_dword v225, v72, s[4:5]
	v_mov_b32_e32 v72, v224
	s_waitcnt lgkmcnt(0)
	s_barrier
	s_nop 0
	v_ashrrev_i32_e32 v118, 3, v72
	v_and_b32_e32 v79, 15, v72
	v_bfe_u32 v80, v72, 4, 2
	v_lshrrev_b32_e32 v85, 2, v72
	v_bfi_b32 v72, -16, v118, v72
	v_lshlrev_b32_e32 v93, 4, v80
	v_mul_lo_u32 v72, v72, s30
	v_add3_u32 v114, 0, v72, v93
	ds_read_b128 v[72:75], v114
	v_and_or_b32 v79, v85, 16, v79
	v_mul_u32_u24_e32 v85, 0x110, v79
	v_add3_u32 v85, s16, v85, v93
	ds_read_b128 v[94:97], v85
	ds_read_b128 v[98:101], v85 offset:64
	ds_read_b128 v[102:105], v114 offset:64
	s_waitcnt lgkmcnt(2)
	v_mfma_f32_16x16x32_bf16 v[72:75], v[72:75], v[94:97], 0
	ds_read_b128 v[106:109], v114 offset:17408
	ds_read_b128 v[110:113], v114 offset:17472
	v_mul_u32_u24_e32 v79, 0x48, v79
	v_lshlrev_b32_e32 v79, 1, v79
	s_waitcnt lgkmcnt(2)
	v_mfma_f32_16x16x32_bf16 v[72:75], v[102:105], v[98:101], v[72:75]
	ds_read_b128 v[102:105], v114 offset:128
	v_lshlrev_b32_e32 v80, 3, v80
	v_add_u32_e32 v93, 0, v79
	s_waitcnt lgkmcnt(2)
	v_mfma_f32_16x16x32_bf16 v[94:97], v[106:109], v[94:97], 0
	s_waitcnt lgkmcnt(1)
	v_mfma_f32_16x16x32_bf16 v[94:97], v[110:113], v[98:101], v[94:97]
	ds_read_b128 v[98:101], v85 offset:128
	ds_read_b128 v[106:109], v85 offset:192
	ds_read_b128 v[110:113], v114 offset:192
	v_and_b32_e32 v85, -16, v118
	v_lshlrev_b32_e32 v85, 1, v85
	s_waitcnt lgkmcnt(2)
	v_mfma_f32_16x16x32_bf16 v[72:75], v[102:105], v[98:101], v[72:75]
	ds_read_b128 v[102:105], v114 offset:17536
	ds_read_b128 v[114:117], v114 offset:17600
	v_add3_u32 v93, v93, v85, v80
	s_waitcnt lgkmcnt(1)
	v_mfma_f32_16x16x32_bf16 v[94:97], v[102:105], v[98:101], v[94:97]
	ds_read_b64 v[98:99], v93 offset:62464
	s_waitcnt lgkmcnt(0)
	v_lshlrev_b32_e32 v100, 16, v98
	v_mfma_f32_16x16x32_bf16 v[72:75], v[110:113], v[106:109], v[72:75]
	v_and_b32_e32 v101, 0xffff0000, v98
	v_lshlrev_b32_e32 v98, 16, v99
	v_and_b32_e32 v99, 0xffff0000, v99
	v_mfma_f32_16x16x32_bf16 v[94:97], v[114:117], v[106:109], v[94:97]
	s_nop 3
	v_add_f32_e64 v72, v100, -v72
	v_add_f32_e64 v73, v101, -v73
	v_pk_add_f32 v[74:75], v[98:99], v[74:75] neg_lo:[0,1] neg_hi:[0,1]
	v_cvt_pk_bf16_f32 v72, v72, v73
	v_cvt_pk_bf16_f32 v73, v74, v75
	v_add_u32_e32 v74, s17, v79
	v_add3_u32 v74, v74, v85, v80
	ds_write_b64 v74, v[72:73]
	v_mov_b32_e32 v72, v224
	s_waitcnt lgkmcnt(0)
	s_barrier
	s_nop 0
	v_ashrrev_i32_e32 v85, 3, v72
	v_ashrrev_i32_e32 v73, 6, v72
	v_and_b32_e32 v93, 15, v72
	v_bfe_u32 v80, v72, 4, 2
	v_bfi_b32 v72, -16, v85, v72
	v_lshlrev_b32_e32 v75, 4, v80
	v_mul_lo_u32 v72, v72, s31
	v_mul_u32_u24_e32 v74, 0x90, v93
	v_add3_u32 v122, s20, v72, v75
	v_lshl_or_b32 v72, v73, 4, v93
	v_and_b32_e32 v126, 1, v73
	v_add3_u32 v79, s17, v74, v75
	v_mul_lo_u32 v72, v72, s31
	v_add3_u32 v127, s19, v72, v75
	ds_read_b128 v[72:75], v79
	ds_read_b128 v[98:101], v79 offset:2304
	ds_read_b128 v[102:105], v122
	ds_read_b128 v[106:109], v127
	ds_read_b128 v[110:113], v79 offset:64
	ds_read_b128 v[114:117], v79 offset:2368
	v_cmp_eq_u32_e32 vcc, 0, v126
	ds_read_b128 v[122:125], v122 offset:64
	s_waitcnt vmcnt(18)
	v_pk_mul_f32 v[70:71], v[78:79], v[70:71] op_sel_hi:[0,1]
	s_waitcnt lgkmcnt(5)
	v_cndmask_b32_e32 v121, v101, v75, vcc
	v_cndmask_b32_e32 v120, v100, v74, vcc
	v_cndmask_b32_e32 v119, v99, v73, vcc
	v_cndmask_b32_e32 v118, v98, v72, vcc
	v_pk_mul_f32 v[68:69], v[78:79], v[68:69] op_sel_hi:[0,1]
	v_pk_mul_f32 v[66:67], v[78:79], v[66:67] op_sel_hi:[0,1]
	s_waitcnt lgkmcnt(4)
	v_mfma_f32_16x16x32_bf16 v[94:97], v[102:105], v[118:121], v[94:97]
	ds_read_b128 v[102:105], v127 offset:64
	v_pk_mul_f32 v[64:65], v[78:79], v[64:65] op_sel_hi:[0,1]
	v_mov_b32_e32 v78, v224
	s_waitcnt lgkmcnt(4)
	v_mfma_f32_16x16x32_bf16 v[68:71], v[106:109], v[72:75], v[68:71]
	s_waitcnt lgkmcnt(2)
	v_cndmask_b32_e32 v75, v117, v113, vcc
	v_cndmask_b32_e32 v74, v116, v112, vcc
	v_cndmask_b32_e32 v73, v115, v111, vcc
	v_mfma_f32_16x16x32_bf16 v[64:67], v[106:109], v[98:101], v[64:67]
	v_cndmask_b32_e32 v72, v114, v110, vcc
	v_and_b32_e32 v85, -16, v85
	s_waitcnt lgkmcnt(0)
	v_mfma_f32_16x16x32_bf16 v[68:71], v[102:105], v[110:113], v[68:71]
	v_and_b32_e32 v79, 15, v78
	v_mul_u32_u24_e32 v79, 0x110, v79
	v_lshl_or_b32 v85, v80, 2, v85
	v_mfma_f32_16x16x32_bf16 v[72:75], v[122:125], v[72:75], v[94:97]
	v_lshlrev_b32_e32 v80, 5, v126
	v_cmp_gt_i32_e32 vcc, 64, v85
	s_nop 0
	v_ashrrev_i32_e32 v94, 2, v78
	v_mfma_f32_16x16x32_bf16 v[64:67], v[102:105], v[114:117], v[64:67]
	v_lshlrev_b32_e32 v94, 1, v94
	v_and_b32_e32 v94, 0xffffffe0, v94
	v_lshrrev_b32_e32 v78, 1, v78
	v_add_u32_e32 v94, s16, v94
	v_and_b32_e32 v78, 24, v78
	v_add3_u32 v94, v94, v78, v79
	v_cvt_pk_bf16_f32 v79, v70, v71
	v_cvt_pk_bf16_f32 v78, v68, v69
	ds_write_b64 v94, v[78:79]
	v_cvt_pk_bf16_f32 v79, v66, v67
	v_cvt_pk_bf16_f32 v78, v64, v65
	ds_write_b64 v94, v[78:79] offset:4352
	v_lshl_add_u64 v[78:79], s[6:7], 0, v[80:81]
	v_lshlrev_b32_e32 v80, 1, v93
	v_lshl_add_u64 v[78:79], v[78:79], 0, v[80:81]
	s_and_saveexec_b64 s[12:13], vcc
	s_cbranch_execz .LBB0_1609
	s_add_i32 s8, s18, s33
	v_add_u32_e32 v80, s8, v85
	v_add_u32_e32 v94, 0x90, v80
	v_ashrrev_i32_e32 v95, 31, v94
	v_lshlrev_b64 v[94:95], 12, v[94:95]
	v_lshl_add_u64 v[94:95], v[78:79], 0, v[94:95]
	v_cvt_pk_bf16_f32 v72, v72, s0
	global_store_short v[94:95], v72, off

; __device__ __forceinline__ void step_part1(char* sm, int off_ut, f32x4& o) {
;   const int tid_ = opq(threadIdx.x);
;   const int lane = tid_ & 63, w = tid_ >> 6, r = lane & 15, q = lane >> 4;
;   const int mj = w >> 1, nd = w & 1;
;   const bfraw* wl = (const bfraw*)(sm + L_W);
;   const bfraw* qg = (const bfraw*)(sm + L_QG);
;   const bfraw* uT = (const bfraw*)(sm + off_ut);
;   const bfraw* St = (const bfraw*)(sm + L_ST);
;   bfraw* dltT = (bfraw*)(sm + L_DLT);
;   f32x4 dl = (f32x4){0.f, 0.f, 0.f, 0.f};
;   o = (f32x4){0.f, 0.f, 0.f, 0.f};
; #pragma unroll
;   for (int kk = 0; kk < 4; ++kk) {
;     bf16x8 sb = *(const bf16x8*)(St + (nd * 16 + r) * 136 + kk * 32 + q * 8);
;     bf16x8 aw = *(const bf16x8*)(wl + (mj * 16 + r) * 136 + kk * 32 + q * 8);
;     bf16x8 aq = *(const bf16x8*)(qg + (mj * 16 + r) * 136 + kk * 32 + q * 8);
;     dl = mfma16(aw, sb, dl);
;     o = mfma16(aq, sb, o);
;   }
;   uint2 uv = *(const uint2*)(uT + (nd * 16 + r) * 72 + mj * 16 + q * 4);
;   uint2 dv;
;   dv.x = pack2(lo2f(uv.x) - dl[0], hi2f(uv.x) - dl[1]);
;   dv.y = pack2(lo2f(uv.y) - dl[2], hi2f(uv.y) - dl[3]);
;   *(uint2*)(dltT + (nd * 16 + r) * 72 + mj * 16 + q * 4) = dv;
; }
; __device__ __forceinline__ void step_part2(const Params& p, char* sm, int off_kgt, int off_qk, int h, int s, int grow0, int nvalid,
;                                            float gl, f32x4& o, f32x4 (&S)[2]) {
;   const int tid_ = opq(threadIdx.x);
;   const int lane = tid_ & 63, w = tid_ >> 6, r = lane & 15, q = lane >> 4;
;   const int mj = w >> 1, nd = w & 1;
;   const bfraw* kgT = (const bfraw*)(sm + off_kgt);
;   const bfraw* qk = (const bfraw*)(sm + off_qk);
;   const bfraw* dltT = (const bfraw*)(sm + L_DLT);
; #pragma unroll
;   for (int g = 0; g < 4; ++g) { S[0][g] *= gl; S[1][g] *= gl; }
; #pragma unroll
;   for (int kk = 0; kk < 2; ++kk) {
;     bf16x8 d0 = *(const bf16x8*)(dltT + (r) * 72 + kk * 32 + q * 8);
;     bf16x8 d1 = *(const bf16x8*)(dltT + (16 + r) * 72 + kk * 32 + q * 8);
;     bf16x8 aqk = *(const bf16x8*)(qk + (mj * 16 + r) * 72 + kk * 32 + q * 8);
;     bf16x8 ak = *(const bf16x8*)(kgT + (w * 16 + r) * 72 + kk * 32 + q * 8);
;     o = mfma16(aqk, nd ? d1 : d0, o);
;     S[0] = mfma16(ak, d0, S[0]);
;     S[1] = mfma16(ak, d1, S[1]);
;   }
;   write_St2(S, sm);
;   bfraw* OB = (bfraw*)(p.ws + WS_B1);
; #pragma unroll
;   for (int g = 0; g < 4; ++g) {
.LBB0_4341:
	s_or_b64 exec, exec, s[10:11]
	s_mul_i32 s21, s14, 0x81
	s_add_i32 s28, s21, 3
	s_lshl_b32 s10, s28, 2
	s_or_b32 s13, s10, s15
	s_mul_i32 s10, s13, 0x12000
	s_mul_hi_u32 s11, s13, 0x12000
	s_add_u32 s10, s8, s10
	s_addc_u32 s11, s9, s11
	s_waitcnt vmcnt(10)
	v_lshl_add_u64 v[56:57], v[82:83], 1, s[10:11]
	v_add_co_u32_e32 v40, vcc, 0x2000, v56
	s_nop 1
	v_addc_co_u32_e32 v41, vcc, 0, v57, vcc
	v_add_co_u32_e32 v48, vcc, 0x4000, v56
	global_load_dwordx4 v[32:35], v[56:57], off
	global_load_dwordx4 v[36:39], v[40:41], off
	v_addc_co_u32_e32 v49, vcc, 0, v57, vcc
	v_add_co_u32_e32 v50, vcc, 0x6000, v56
	s_nop 1
	v_addc_co_u32_e32 v51, vcc, 0, v57, vcc
	v_add_co_u32_e32 v58, vcc, 0x8000, v56
	global_load_dwordx4 v[40:43], v[48:49], off
	global_load_dwordx4 v[44:47], v[50:51], off
	v_addc_co_u32_e32 v59, vcc, 0, v57, vcc
	v_add_co_u32_e32 v60, vcc, 0xa000, v56
	s_nop 1
	v_addc_co_u32_e32 v61, vcc, 0, v57, vcc
	v_add_co_u32_e32 v72, vcc, 0xc000, v56
	global_load_dwordx4 v[48:51], v[58:59], off
	global_load_dwordx4 v[52:55], v[60:61], off
	v_addc_co_u32_e32 v73, vcc, 0, v57, vcc
	v_lshl_add_u64 v[56:57], v[56:57], 0, s[0:1]
	v_lshl_add_u64 v[56:57], v[76:77], 1, v[56:57]
	v_add_co_u32_e32 v74, vcc, 0xe000, v56
	s_lshl_b32 s1, s13, 2
	s_nop 0
	v_addc_co_u32_e32 v75, vcc, 0, v57, vcc
	global_load_dwordx4 v[60:63], v[72:73], off
	global_load_dwordx4 v[56:59], v[74:75], off
	v_mov_b32_e32 v72, s1
	global_load_dword v225, v72, s[4:5]
	v_mov_b32_e32 v72, v224
	s_waitcnt lgkmcnt(0)
	s_barrier
	s_movk_i32 s1, 0x110
	v_ashrrev_i32_e32 v116, 3, v72
	v_and_b32_e32 v79, 15, v72
	v_bfe_u32 v81, v72, 4, 2
	v_lshrrev_b32_e32 v85, 2, v72
	v_bfi_b32 v72, -16, v116, v72
	v_lshlrev_b32_e32 v91, 4, v81
	v_mul_lo_u32 v72, v72, s1
	v_add3_u32 v112, 0, v72, v91
	ds_read_b128 v[72:75], v112
	v_and_or_b32 v79, v85, 16, v79
	v_mul_u32_u24_e32 v85, 0x110, v79
	v_add3_u32 v85, s16, v85, v91
	ds_read_b128 v[92:95], v85
	ds_read_b128 v[96:99], v85 offset:64
	ds_read_b128 v[100:103], v112 offset:64
	s_waitcnt lgkmcnt(2)
	v_mfma_f32_16x16x32_bf16 v[72:75], v[72:75], v[92:95], 0
	ds_read_b128 v[104:107], v112 offset:17408
	ds_read_b128 v[108:111], v112 offset:17472
	v_mul_u32_u24_e32 v79, 0x48, v79
	v_lshlrev_b32_e32 v79, 1, v79
	s_waitcnt lgkmcnt(2)
	v_mfma_f32_16x16x32_bf16 v[72:75], v[100:103], v[96:99], v[72:75]
	ds_read_b128 v[100:103], v112 offset:128
	v_lshlrev_b32_e32 v81, 3, v81
	v_add_u32_e32 v91, 0, v79
	s_waitcnt lgkmcnt(2)
	v_mfma_f32_16x16x32_bf16 v[92:95], v[104:107], v[92:95], 0
	s_movk_i32 s1, 0x90
	s_waitcnt lgkmcnt(1)
	v_mfma_f32_16x16x32_bf16 v[92:95], v[108:111], v[96:99], v[92:95]
	ds_read_b128 v[96:99], v85 offset:128
	ds_read_b128 v[104:107], v85 offset:192
	ds_read_b128 v[108:111], v112 offset:192
	v_and_b32_e32 v85, -16, v116
	v_lshlrev_b32_e32 v85, 1, v85
	s_waitcnt lgkmcnt(2)
	v_mfma_f32_16x16x32_bf16 v[72:75], v[100:103], v[96:99], v[72:75]
	ds_read_b128 v[100:103], v112 offset:17536
	ds_read_b128 v[112:115], v112 offset:17600
	v_add3_u32 v91, v91, v85, v81
	s_waitcnt lgkmcnt(1)
	v_mfma_f32_16x16x32_bf16 v[92:95], v[100:103], v[96:99], v[92:95]
	ds_read_b64 v[96:97], v91 offset:62464
	s_waitcnt lgkmcnt(0)
	v_lshlrev_b32_e32 v98, 16, v96
	v_mfma_f32_16x16x32_bf16 v[72:75], v[108:111], v[104:107], v[72:75]
	v_and_b32_e32 v99, 0xffff0000, v96
	v_lshlrev_b32_e32 v96, 16, v97
	v_and_b32_e32 v97, 0xffff0000, v97
	v_mfma_f32_16x16x32_bf16 v[92:95], v[112:115], v[104:107], v[92:95]
	s_nop 3
	v_add_f32_e64 v72, v98, -v72
	v_add_f32_e64 v73, v99, -v73
	v_pk_add_f32 v[74:75], v[96:97], v[74:75] neg_lo:[0,1] neg_hi:[0,1]
	v_cvt_pk_bf16_f32 v72, v72, v73
	v_cvt_pk_bf16_f32 v73, v74, v75
	v_add_u32_e32 v74, s17, v79
	v_add3_u32 v74, v74, v85, v81
	ds_write_b64 v74, v[72:73]
	v_mov_b32_e32 v72, v224
	s_waitcnt lgkmcnt(0)
	s_barrier
	s_nop 0
	v_ashrrev_i32_e32 v124, 3, v72
	v_ashrrev_i32_e32 v73, 6, v72
	v_and_b32_e32 v81, 15, v72
	v_bfe_u32 v79, v72, 4, 2
	v_bfi_b32 v72, -16, v124, v72
	v_lshlrev_b32_e32 v75, 4, v79
	v_mul_lo_u32 v72, v72, s1
	v_mul_u32_u24_e32 v74, 0x90, v81
	v_add3_u32 v120, s20, v72, v75
	v_lshl_or_b32 v72, v73, 4, v81
	v_and_b32_e32 v91, 1, v73
	v_add3_u32 v85, s17, v74, v75
	v_mul_lo_u32 v72, v72, s1
	v_add3_u32 v125, s19, v72, v75
	ds_read_b128 v[72:75], v85
	ds_read_b128 v[96:99], v85 offset:2304
	ds_read_b128 v[100:103], v120
	ds_read_b128 v[104:107], v125
	ds_read_b128 v[108:111], v85 offset:64
	ds_read_b128 v[112:115], v85 offset:2368
	v_cmp_eq_u32_e32 vcc, 0, v91
	ds_read_b128 v[120:123], v120 offset:64
	s_waitcnt vmcnt(18)
	v_pk_mul_f32 v[70:71], v[84:85], v[70:71] op_sel_hi:[0,1]
	s_waitcnt lgkmcnt(5)
	v_cndmask_b32_e32 v119, v99, v75, vcc
	v_cndmask_b32_e32 v118, v98, v74, vcc
	v_cndmask_b32_e32 v117, v97, v73, vcc
	v_cndmask_b32_e32 v116, v96, v72, vcc
	v_pk_mul_f32 v[68:69], v[84:85], v[68:69] op_sel_hi:[0,1]
	v_pk_mul_f32 v[66:67], v[84:85], v[66:67] op_sel_hi:[0,1]
	s_waitcnt lgkmcnt(4)
	v_mfma_f32_16x16x32_bf16 v[92:95], v[100:103], v[116:119], v[92:95]
	ds_read_b128 v[100:103], v125 offset:64
	v_pk_mul_f32 v[64:65], v[84:85], v[64:65] op_sel_hi:[0,1]
	v_mov_b32_e32 v84, v224
	s_waitcnt lgkmcnt(4)
	v_mfma_f32_16x16x32_bf16 v[68:71], v[104:107], v[72:75], v[68:71]
	s_waitcnt lgkmcnt(2)
	v_cndmask_b32_e32 v75, v115, v111, vcc
	v_cndmask_b32_e32 v74, v114, v110, vcc
	v_cndmask_b32_e32 v73, v113, v109, vcc
	v_mfma_f32_16x16x32_bf16 v[64:67], v[104:107], v[96:99], v[64:67]
	v_cndmask_b32_e32 v72, v112, v108, vcc
	s_add_i32 s1, s18, 16
	s_waitcnt lgkmcnt(0)
	v_mfma_f32_16x16x32_bf16 v[68:71], v[100:103], v[108:111], v[68:71]
	v_and_b32_e32 v85, 15, v84
	v_mul_u32_u24_e32 v85, 0x110, v85
	v_mfma_f32_16x16x32_bf16 v[72:75], v[120:123], v[72:75], v[92:95]
	s_nop 2
	v_ashrrev_i32_e32 v93, 2, v84
	v_mfma_f32_16x16x32_bf16 v[64:67], v[100:103], v[112:115], v[64:67]
	v_lshlrev_b32_e32 v93, 1, v93
	v_and_b32_e32 v93, 0xffffffe0, v93
	v_lshrrev_b32_e32 v84, 1, v84
	v_add_u32_e32 v93, s16, v93
	v_and_b32_e32 v84, 24, v84
	v_add3_u32 v93, v93, v84, v85
	v_cvt_pk_bf16_f32 v85, v70, v71
	v_cvt_pk_bf16_f32 v84, v68, v69
	ds_write_b64 v93, v[84:85]
	v_cvt_pk_bf16_f32 v85, v66, v67
	v_cvt_pk_bf16_f32 v84, v64, v65
	v_and_b32_e32 v92, -16, v124
	ds_write_b64 v93, v[84:85] offset:4352
	v_lshlrev_b32_e32 v84, 5, v91
	v_mov_b32_e32 v85, 0
	v_lshl_or_b32 v79, v79, 2, v92
	v_lshl_add_u64 v[92:93], s[6:7], 0, v[84:85]
	v_lshlrev_b32_e32 v84, 1, v81
	v_lshl_add_u64 v[84:85], v[92:93], 0, v[84:85]
	v_cmp_gt_i32_e32 vcc, 64, v79
	s_and_saveexec_b64 s[10:11], vcc
	s_cbranch_execz .LBB0_4343
	v_add_u32_e32 v92, s1, v79
	v_ashrrev_i32_e32 v93, 31, v92
	v_lshlrev_b64 v[92:93], 12, v[92:93]
	v_lshl_add_u64 v[92:93], v[84:85], 0, v[92:93]
	v_cvt_pk_bf16_f32 v72, v72, s0
	global_store_short v[92:93], v72, off

; __device__ __forceinline__ void step_part1(char* sm, int off_ut, f32x4& o) {
;   const int tid_ = opq(threadIdx.x);
;   const int lane = tid_ & 63, w = tid_ >> 6, r = lane & 15, q = lane >> 4;
;   const int mj = w >> 1, nd = w & 1;
;   const bfraw* wl = (const bfraw*)(sm + L_W);
;   const bfraw* qg = (const bfraw*)(sm + L_QG);
;   const bfraw* uT = (const bfraw*)(sm + off_ut);
;   const bfraw* St = (const bfraw*)(sm + L_ST);
;   bfraw* dltT = (bfraw*)(sm + L_DLT);
;   f32x4 dl = (f32x4){0.f, 0.f, 0.f, 0.f};
;   o = (f32x4){0.f, 0.f, 0.f, 0.f};
; #pragma unroll
;   for (int kk = 0; kk < 4; ++kk) {
;     bf16x8 sb = *(const bf16x8*)(St + (nd * 16 + r) * 136 + kk * 32 + q * 8);
;     bf16x8 aw = *(const bf16x8*)(wl + (mj * 16 + r) * 136 + kk * 32 + q * 8);
;     bf16x8 aq = *(const bf16x8*)(qg + (mj * 16 + r) * 136 + kk * 32 + q * 8);
;     dl = mfma16(aw, sb, dl);
;     o = mfma16(aq, sb, o);
;   }
;   uint2 uv = *(const uint2*)(uT + (nd * 16 + r) * 72 + mj * 16 + q * 4);
;   uint2 dv;
;   dv.x = pack2(lo2f(uv.x) - dl[0], hi2f(uv.x) - dl[1]);
;   dv.y = pack2(lo2f(uv.y) - dl[2], hi2f(uv.y) - dl[3]);
;   *(uint2*)(dltT + (nd * 16 + r) * 72 + mj * 16 + q * 4) = dv;
; }
; __device__ __forceinline__ void step_part2(const Params& p, char* sm, int off_kgt, int off_qk, int h, int s, int grow0, int nvalid,
;                                            float gl, f32x4& o, f32x4 (&S)[2]) {
;   const int tid_ = opq(threadIdx.x);
;   const int lane = tid_ & 63, w = tid_ >> 6, r = lane & 15, q = lane >> 4;
;   const int mj = w >> 1, nd = w & 1;
;   const bfraw* kgT = (const bfraw*)(sm + off_kgt);
;   const bfraw* qk = (const bfraw*)(sm + off_qk);
;   const bfraw* dltT = (const bfraw*)(sm + L_DLT);
; #pragma unroll
;   for (int g = 0; g < 4; ++g) { S[0][g] *= gl; S[1][g] *= gl; }
; #pragma unroll
;   for (int kk = 0; kk < 2; ++kk) {
;     bf16x8 d0 = *(const bf16x8*)(dltT + (r) * 72 + kk * 32 + q * 8);
;     bf16x8 d1 = *(const bf16x8*)(dltT + (16 + r) * 72 + kk * 32 + q * 8);
;     bf16x8 aqk = *(const bf16x8*)(qk + (mj * 16 + r) * 72 + kk * 32 + q * 8);
;     bf16x8 ak = *(const bf16x8*)(kgT + (w * 16 + r) * 72 + kk * 32 + q * 8);
;     o = mfma16(aqk, nd ? d1 : d0, o);
;     S[0] = mfma16(ak, d0, S[0]);
;     S[1] = mfma16(ak, d1, S[1]);
;   }
;   write_St2(S, sm);
;   bfraw* OB = (bfraw*)(p.ws + WS_B1);
; #pragma unroll
;   for (int g = 0; g < 4; ++g) {
.LBB0_4365:
	s_or_b64 exec, exec, s[12:13]
	s_min_u32 s8, s34, 0x7d
	s_add_i32 s8, s8, s28
	s_lshl_b32 s8, s8, 2
	s_or_b32 s8, s8, s15
	s_waitcnt vmcnt(10)
	v_mov_b32_e32 v78, v225
	v_mad_u64_u32 v[56:57], s[12:13], s8, v91, v[82:83]
	v_add_co_u32_e32 v40, vcc, 0x2000, v56
	s_lshl_b32 s8, s8, 2
	s_nop 0
	v_addc_co_u32_e32 v41, vcc, 0, v57, vcc
	global_load_dwordx4 v[32:35], v[56:57], off
	global_load_dwordx4 v[36:39], v[40:41], off
	v_add_co_u32_e32 v40, vcc, 0x4000, v56
	v_mov_b32_e32 v72, s8
	s_nop 0
	v_addc_co_u32_e32 v41, vcc, 0, v57, vcc
	v_add_co_u32_e32 v44, vcc, 0x6000, v56
	s_nop 1
	v_addc_co_u32_e32 v45, vcc, 0, v57, vcc
	v_add_co_u32_e32 v48, vcc, 0x8000, v56
	global_load_dwordx4 v[40:43], v[40:41], off
	s_nop 0
	global_load_dwordx4 v[44:47], v[44:45], off
	v_addc_co_u32_e32 v49, vcc, 0, v57, vcc
	v_add_co_u32_e32 v52, vcc, 0xa000, v56
	s_nop 1
	v_addc_co_u32_e32 v53, vcc, 0, v57, vcc
	v_add_co_u32_e32 v58, vcc, 0xc000, v56
	global_load_dwordx4 v[48:51], v[48:49], off
	s_nop 0
	global_load_dwordx4 v[52:55], v[52:53], off
	v_addc_co_u32_e32 v59, vcc, 0, v57, vcc
	v_lshl_add_u64 v[56:57], v[56:57], 0, s[0:1]
	v_lshl_add_u64 v[56:57], v[76:77], 1, v[56:57]
	v_add_co_u32_e32 v56, vcc, 0xe000, v56
	s_nop 1
	v_addc_co_u32_e32 v57, vcc, 0, v57, vcc
	global_load_dwordx4 v[60:63], v[58:59], off
	s_nop 0
	global_load_dwordx4 v[56:59], v[56:57], off
	s_nop 0
	global_load_dword v225, v72, s[4:5]
	v_mov_b32_e32 v72, v224
	s_waitcnt lgkmcnt(0)
	s_barrier
	s_nop 0
	v_ashrrev_i32_e32 v118, 3, v72
	v_and_b32_e32 v79, 15, v72
	v_bfe_u32 v80, v72, 4, 2
	v_lshrrev_b32_e32 v85, 2, v72
	v_bfi_b32 v72, -16, v118, v72
	v_lshlrev_b32_e32 v93, 4, v80
	v_mul_lo_u32 v72, v72, s30
	v_add3_u32 v114, 0, v72, v93
	ds_read_b128 v[72:75], v114
	v_and_or_b32 v79, v85, 16, v79
	v_mul_u32_u24_e32 v85, 0x110, v79
	v_add3_u32 v85, s16, v85, v93
	ds_read_b128 v[94:97], v85
	ds_read_b128 v[98:101], v85 offset:64
	ds_read_b128 v[102:105], v114 offset:64
	s_waitcnt lgkmcnt(2)
	v_mfma_f32_16x16x32_bf16 v[72:75], v[72:75], v[94:97], 0
	ds_read_b128 v[106:109], v114 offset:17408
	ds_read_b128 v[110:113], v114 offset:17472
	v_mul_u32_u24_e32 v79, 0x48, v79
	v_lshlrev_b32_e32 v79, 1, v79
	s_waitcnt lgkmcnt(2)
	v_mfma_f32_16x16x32_bf16 v[72:75], v[102:105], v[98:101], v[72:75]
	ds_read_b128 v[102:105], v114 offset:128
	v_lshlrev_b32_e32 v80, 3, v80
	v_add_u32_e32 v93, 0, v79
	s_waitcnt lgkmcnt(2)
	v_mfma_f32_16x16x32_bf16 v[94:97], v[106:109], v[94:97], 0
	s_waitcnt lgkmcnt(1)
	v_mfma_f32_16x16x32_bf16 v[94:97], v[110:113], v[98:101], v[94:97]
	ds_read_b128 v[98:101], v85 offset:128
	ds_read_b128 v[106:109], v85 offset:192
	ds_read_b128 v[110:113], v114 offset:192
	v_and_b32_e32 v85, -16, v118
	v_lshlrev_b32_e32 v85, 1, v85
	s_waitcnt lgkmcnt(2)
	v_mfma_f32_16x16x32_bf16 v[72:75], v[102:105], v[98:101], v[72:75]
	ds_read_b128 v[102:105], v114 offset:17536
	ds_read_b128 v[114:117], v114 offset:17600
	v_add3_u32 v93, v93, v85, v80
	s_waitcnt lgkmcnt(1)
	v_mfma_f32_16x16x32_bf16 v[94:97], v[102:105], v[98:101], v[94:97]
	ds_read_b64 v[98:99], v93 offset:62464
	s_waitcnt lgkmcnt(0)
	v_lshlrev_b32_e32 v100, 16, v98
	v_mfma_f32_16x16x32_bf16 v[72:75], v[110:113], v[106:109], v[72:75]
	v_and_b32_e32 v101, 0xffff0000, v98
	v_lshlrev_b32_e32 v98, 16, v99
	v_and_b32_e32 v99, 0xffff0000, v99
	v_mfma_f32_16x16x32_bf16 v[94:97], v[114:117], v[106:109], v[94:97]
	s_nop 3
	v_add_f32_e64 v72, v100, -v72
	v_add_f32_e64 v73, v101, -v73
	v_pk_add_f32 v[74:75], v[98:99], v[74:75] neg_lo:[0,1] neg_hi:[0,1]
	v_cvt_pk_bf16_f32 v72, v72, v73
	v_cvt_pk_bf16_f32 v73, v74, v75
	v_add_u32_e32 v74, s17, v79
	v_add3_u32 v74, v74, v85, v80
	ds_write_b64 v74, v[72:73]
	v_mov_b32_e32 v72, v224
	s_waitcnt lgkmcnt(0)
	s_barrier
	s_nop 0
	v_ashrrev_i32_e32 v85, 3, v72
	v_ashrrev_i32_e32 v73, 6, v72
	v_and_b32_e32 v93, 15, v72
	v_bfe_u32 v80, v72, 4, 2
	v_bfi_b32 v72, -16, v85, v72
	v_lshlrev_b32_e32 v75, 4, v80
	v_mul_lo_u32 v72, v72, s31
	v_mul_u32_u24_e32 v74, 0x90, v93
	v_add3_u32 v122, s20, v72, v75
	v_lshl_or_b32 v72, v73, 4, v93
	v_and_b32_e32 v126, 1, v73
	v_add3_u32 v79, s17, v74, v75
	v_mul_lo_u32 v72, v72, s31
	v_add3_u32 v127, s19, v72, v75
	ds_read_b128 v[72:75], v79
	ds_read_b128 v[98:101], v79 offset:2304
	ds_read_b128 v[102:105], v122
	ds_read_b128 v[106:109], v127
	ds_read_b128 v[110:113], v79 offset:64
	ds_read_b128 v[114:117], v79 offset:2368
	v_cmp_eq_u32_e32 vcc, 0, v126
	ds_read_b128 v[122:125], v122 offset:64
	s_waitcnt vmcnt(18)
	v_pk_mul_f32 v[70:71], v[78:79], v[70:71] op_sel_hi:[0,1]
	s_waitcnt lgkmcnt(5)
	v_cndmask_b32_e32 v121, v101, v75, vcc
	v_cndmask_b32_e32 v120, v100, v74, vcc
	v_cndmask_b32_e32 v119, v99, v73, vcc
	v_cndmask_b32_e32 v118, v98, v72, vcc
	v_pk_mul_f32 v[68:69], v[78:79], v[68:69] op_sel_hi:[0,1]
	v_pk_mul_f32 v[66:67], v[78:79], v[66:67] op_sel_hi:[0,1]
	s_waitcnt lgkmcnt(4)
	v_mfma_f32_16x16x32_bf16 v[94:97], v[102:105], v[118:121], v[94:97]
	ds_read_b128 v[102:105], v127 offset:64
	v_pk_mul_f32 v[64:65], v[78:79], v[64:65] op_sel_hi:[0,1]
	v_mov_b32_e32 v78, v224
	s_waitcnt lgkmcnt(4)
	v_mfma_f32_16x16x32_bf16 v[68:71], v[106:109], v[72:75], v[68:71]
	s_waitcnt lgkmcnt(2)
	v_cndmask_b32_e32 v75, v117, v113, vcc
	v_cndmask_b32_e32 v74, v116, v112, vcc
	v_cndmask_b32_e32 v73, v115, v111, vcc
	v_mfma_f32_16x16x32_bf16 v[64:67], v[106:109], v[98:101], v[64:67]
	v_cndmask_b32_e32 v72, v114, v110, vcc
	v_and_b32_e32 v85, -16, v85
	s_waitcnt lgkmcnt(0)
	v_mfma_f32_16x16x32_bf16 v[68:71], v[102:105], v[110:113], v[68:71]
	v_and_b32_e32 v79, 15, v78
	v_mul_u32_u24_e32 v79, 0x110, v79
	v_lshl_or_b32 v85, v80, 2, v85
	v_mfma_f32_16x16x32_bf16 v[72:75], v[122:125], v[72:75], v[94:97]
	v_lshlrev_b32_e32 v80, 5, v126
	v_cmp_gt_i32_e32 vcc, 64, v85
	s_nop 0
	v_ashrrev_i32_e32 v94, 2, v78
	v_mfma_f32_16x16x32_bf16 v[64:67], v[102:105], v[114:117], v[64:67]
	v_lshlrev_b32_e32 v94, 1, v94
	v_and_b32_e32 v94, 0xffffffe0, v94
	v_lshrrev_b32_e32 v78, 1, v78
	v_add_u32_e32 v94, s16, v94
	v_and_b32_e32 v78, 24, v78
	v_add3_u32 v94, v94, v78, v79
	v_cvt_pk_bf16_f32 v79, v70, v71
	v_cvt_pk_bf16_f32 v78, v68, v69
	ds_write_b64 v94, v[78:79]
	v_cvt_pk_bf16_f32 v79, v66, v67
	v_cvt_pk_bf16_f32 v78, v64, v65
	ds_write_b64 v94, v[78:79] offset:4352
	v_lshl_add_u64 v[78:79], s[6:7], 0, v[80:81]
	v_lshlrev_b32_e32 v80, 1, v93
	v_lshl_add_u64 v[78:79], v[78:79], 0, v[80:81]
	s_and_saveexec_b64 s[12:13], vcc
	s_cbranch_execz .LBB0_4367
	s_add_i32 s8, s18, s33
	v_add_u32_e32 v80, s8, v85
	v_add_u32_e32 v94, 0x90, v80
	v_ashrrev_i32_e32 v95, 31, v94
	v_lshlrev_b64 v[94:95], 12, v[94:95]
	v_lshl_add_u64 v[94:95], v[78:79], 0, v[94:95]
	v_cvt_pk_bf16_f32 v72, v72, s0
	global_store_short v[94:95], v72, off
